# diff attention loop tail: last key step gets its own copy of the final PV MFMA + row-sum bookkeeping (no second exit test on the steady-state path); one scalar move folded
# speedup vs baseline: 1.0063x; 1.0003x over previous
; template <bool HAS_QK, bool HAS_PV> ...
;     ...
;     if (HAS_PV) {
; #pragma unroll
;         for (int ks = 2; ks < 4; ++ks)
; #pragma unroll
;             for (int c4 = 0; c4 < 4; ++c4) { const bf16x8 vf = vfrag(Vp, vb0, vb1, ks, c4); O[c4] = __builtin_amdgcn_mfma_f32_32x32x16_bf16(vf, P[ks], O[c4], 0, 0, 0); }
;     }
;     if (HAS_QK) {
;         float sum0 = 0.f, sum1 = 0.f;
; #pragma unroll
;         for (int r = 0; r < 16; ++r) { s0[r] = __builtin_amdgcn_exp2f(s0[r]); s1[r] = __builtin_amdgcn_exp2f(s1[r]); sum0 += s0[r]; sum1 += s1[r]; }
; #pragma unroll
;         for (int sp = 0; sp < 2; ++sp) {
;             u32x4 w0, w1;
;             w0.x = cvtpk(s0[8 * sp + 0], s0[8 * sp + 1]); w0.y = cvtpk(s0[8 * sp + 2], s0[8 * sp + 3]); w0.z = cvtpk(s0[8 * sp + 4], s0[8 * sp + 5]); w0.w = cvtpk(s0[8 * sp + 6], s0[8 * sp + 7]);
;             w1.x = cvtpk(s1[8 * sp + 0], s1[8 * sp + 1]); w1.y = cvtpk(s1[8 * sp + 2], s1[8 * sp + 3]); w1.z = cvtpk(s1[8 * sp + 4], s1[8 * sp + 5]); w1.w = cvtpk(s1[8 * sp + 6], s1[8 * sp + 7]);
;             P[sp] = __builtin_bit_cast(bf16x8, w0); P[2 + sp] = __builtin_bit_cast(bf16x8, w1);
;         }
;         if (need && !first) {
; #pragma unroll
;             for (int e = 0; e < 4; ++e) O[e] *= f;
;         }
;         lrun = lrun * f + (sum0 + sum1);
;     ...
;     for (int st = 0; st < ns; ++st) {
;         const unsigned bb = (st & 1) * 65536u;
;         if (st + 1 < ns) DIFF_DMA2(st + 1, ((st + 1) & 1) * 65536u);
;         const LAS unsigned char* KA = lds + bb + cmap * 1024; const LAS unsigned char* VA = lds + bb + 16384;
;         const LAS unsigned char* KB = lds + bb + 32768 + cmap * 1024; const LAS unsigned char* VB = lds + bb + 49152;
;         { const int kq = st * 128;
;           const bool farR = (kq - q0w - 31 >= 91), farL = (kq + 63 - q0w <= -91), nr = !(farR || farL);
;           diff_step<true, false>(KA, VA, tab, qf, O, P, mrun, lrun, nr ? 0.f : (farR ? tab[256] : tab[0]), kq + ibq, kb0, kb1, vb0, vb1, nr, st == 0); }
;         { const int kq = st * 128 + 64;
;           const bool farR = (kq - q0w - 31 >= 91), farL = (kq + 63 - q0w <= -91), nr = !(farR || farL);
;           diff_step<true, true>(KB, VA, tab, qf, O, P, mrun, lrun, nr ? 0.f : (farR ? tab[256] : tab[0]), kq + ibq, kb0, kb1, vb0, vb1, nr); }
;         diff_step<false, true>(KB, VB, tab, qf, O, P, mrun, lrun, 0.f, 0, kb0, kb1, vb0, vb1, false);
.LBB0_199:
	ds_read_b64_tr_b16 v[220:221], v237 offset:49152
	ds_read_b64_tr_b16 v[222:223], v236 offset:51200
	ds_read_b64_tr_b16 v[224:225], v237 offset:49664
	ds_read_b64_tr_b16 v[226:227], v236 offset:51712
	ds_read_b64_tr_b16 v[228:229], v237 offset:50176
	ds_read_b64_tr_b16 v[230:231], v236 offset:52224
	ds_read_b64_tr_b16 v[232:233], v237 offset:50688
	ds_read_b64_tr_b16 v[234:235], v236 offset:52736
	s_waitcnt lgkmcnt(6)
	v_mfma_f32_32x32x16_bf16 v[64:79], v[220:223], v[182:185], v[64:79]
	ds_read_b64_tr_b16 v[220:221], v237 offset:53248
	ds_read_b64_tr_b16 v[222:223], v236 offset:55296
	v_cvt_pk_bf16_f32 v186, v120, v121
	v_cvt_pk_bf16_f32 v187, v122, v123
	v_cvt_pk_bf16_f32 v188, v124, v125
	v_cvt_pk_bf16_f32 v189, v126, v127
	v_exp_f32_e32 v96, v96
	v_exp_f32_e32 v97, v97
	s_waitcnt lgkmcnt(6)
	v_mfma_f32_32x32x16_bf16 v[48:63], v[224:227], v[182:185], v[48:63]
	ds_read_b64_tr_b16 v[224:225], v237 offset:53760
	ds_read_b64_tr_b16 v[226:227], v236 offset:55808
	v_exp_f32_e32 v98, v98
	v_exp_f32_e32 v99, v99
	v_exp_f32_e32 v100, v100
	s_waitcnt lgkmcnt(6)
	v_mfma_f32_32x32x16_bf16 v[32:47], v[228:231], v[182:185], v[32:47]
	ds_read_b64_tr_b16 v[228:229], v237 offset:54272
	ds_read_b64_tr_b16 v[230:231], v236 offset:56320
	v_exp_f32_e32 v101, v101
	v_exp_f32_e32 v102, v102
	v_exp_f32_e32 v103, v103
	v_cvt_pk_bf16_f32 v10, v96, v97
	v_cvt_pk_bf16_f32 v11, v98, v99
	s_waitcnt lgkmcnt(6)
	v_mfma_f32_32x32x16_bf16 v[16:31], v[232:235], v[182:185], v[16:31]
	ds_read_b64_tr_b16 v[232:233], v237 offset:54784
	ds_read_b64_tr_b16 v[234:235], v236 offset:56832
	v_cvt_pk_bf16_f32 v12, v100, v101
	v_cvt_pk_bf16_f32 v13, v102, v103
	v_exp_f32_e32 v104, v104
	v_exp_f32_e32 v105, v105
	v_exp_f32_e32 v106, v106
	s_waitcnt lgkmcnt(6)
	v_mfma_f32_32x32x16_bf16 v[64:79], v[220:223], v[186:189], v[64:79]
	ds_read_b64_tr_b16 v[220:221], v237 offset:57344
	ds_read_b64_tr_b16 v[222:223], v236 offset:59392
	v_exp_f32_e32 v107, v107
	v_exp_f32_e32 v108, v108
	v_exp_f32_e32 v109, v109
	s_waitcnt lgkmcnt(6)
	v_mfma_f32_32x32x16_bf16 v[48:63], v[224:227], v[186:189], v[48:63]
	ds_read_b64_tr_b16 v[224:225], v237 offset:57856
	ds_read_b64_tr_b16 v[226:227], v236 offset:59904
	v_exp_f32_e32 v110, v110
	v_exp_f32_e32 v111, v111
	v_cvt_pk_bf16_f32 v216, v104, v105
	v_cvt_pk_bf16_f32 v217, v106, v107
	v_cvt_pk_bf16_f32 v218, v108, v109
	v_cvt_pk_bf16_f32 v219, v110, v111
	s_waitcnt lgkmcnt(6)
	v_mfma_f32_32x32x16_bf16 v[32:47], v[228:231], v[186:189], v[32:47]
	ds_read_b64_tr_b16 v[228:229], v237 offset:58368
	ds_read_b64_tr_b16 v[230:231], v236 offset:60416
	v_add_f32_e32 v210, v179, v180
	v_add_f32_e32 v211, v80, v81
	v_add_f32_e32 v212, v112, v113
	v_add_f32_e32 v213, v96, v97
	v_add_f32_e32 v210, v130, v210
	v_add_f32_e32 v211, v82, v211
	v_add_f32_e32 v212, v114, v212
	s_waitcnt lgkmcnt(6)
	v_mfma_f32_32x32x16_bf16 v[16:31], v[232:235], v[186:189], v[16:31]
	ds_read_b64_tr_b16 v[232:233], v237 offset:58880
	ds_read_b64_tr_b16 v[234:235], v236 offset:60928
	v_add_f32_e32 v213, v98, v213
	v_add_f32_e32 v210, v131, v210
	v_add_f32_e32 v211, v83, v211
	v_add_f32_e32 v212, v115, v212
	v_add_f32_e32 v213, v99, v213
	v_add_f32_e32 v210, v132, v210
	v_add_f32_e32 v211, v84, v211
	v_add_f32_e32 v212, v116, v212
	s_waitcnt lgkmcnt(6)
	v_mfma_f32_32x32x16_bf16 v[64:79], v[220:223], v[10:13], v[64:79]
	ds_read_b64_tr_b16 v[220:221], v237 offset:61440
	ds_read_b64_tr_b16 v[222:223], v236 offset:63488
	v_add_f32_e32 v213, v100, v213
	v_add_f32_e32 v210, v133, v210
	v_add_f32_e32 v211, v85, v211
	v_add_f32_e32 v212, v117, v212
	v_add_f32_e32 v213, v101, v213
	v_add_f32_e32 v210, v134, v210
	v_add_f32_e32 v211, v86, v211
	s_waitcnt lgkmcnt(6)
	v_mfma_f32_32x32x16_bf16 v[48:63], v[224:227], v[10:13], v[48:63]
	ds_read_b64_tr_b16 v[224:225], v237 offset:61952
	ds_read_b64_tr_b16 v[226:227], v236 offset:64000
	v_add_f32_e32 v212, v118, v212
	v_add_f32_e32 v213, v102, v213
	v_add_f32_e32 v210, v135, v210
	v_add_f32_e32 v211, v87, v211
	v_add_f32_e32 v212, v119, v212
	v_add_f32_e32 v213, v103, v213
	v_add_f32_e32 v210, v136, v210
	s_waitcnt lgkmcnt(6)
	v_mfma_f32_32x32x16_bf16 v[32:47], v[228:231], v[10:13], v[32:47]
	ds_read_b64_tr_b16 v[228:229], v237 offset:62464
	ds_read_b64_tr_b16 v[230:231], v236 offset:64512
	v_add_f32_e32 v211, v88, v211
	v_add_f32_e32 v212, v120, v212
	v_add_f32_e32 v213, v104, v213
	v_add_f32_e32 v210, v137, v210
	v_add_f32_e32 v211, v89, v211
	v_add_f32_e32 v212, v121, v212
	v_add_f32_e32 v213, v105, v213
	v_add_f32_e32 v210, v138, v210
	s_waitcnt lgkmcnt(6)
	v_mfma_f32_32x32x16_bf16 v[16:31], v[232:235], v[10:13], v[16:31]
	ds_read_b64_tr_b16 v[232:233], v237 offset:62976
	ds_read_b64_tr_b16 v[234:235], v236 offset:65024
	v_add_f32_e32 v211, v90, v211
	v_add_f32_e32 v212, v122, v212
	v_add_f32_e32 v213, v106, v213
	v_add_f32_e32 v210, v139, v210
	v_add_f32_e32 v211, v91, v211
	v_add_f32_e32 v212, v123, v212
	v_add_f32_e32 v213, v107, v213
	s_waitcnt lgkmcnt(6)
	v_mfma_f32_32x32x16_bf16 v[64:79], v[220:223], v[216:219], v[64:79]
	v_add_f32_e32 v210, v140, v210
	v_add_f32_e32 v211, v92, v211
	v_add_f32_e32 v212, v124, v212
	v_add_f32_e32 v213, v108, v213
	v_add_f32_e32 v210, v141, v210
	v_add_f32_e32 v211, v93, v211
	v_add_f32_e32 v212, v125, v212
	s_waitcnt lgkmcnt(4)
	v_mfma_f32_32x32x16_bf16 v[48:63], v[224:227], v[216:219], v[48:63]
	v_add_f32_e32 v213, v109, v213
	v_add_f32_e32 v210, v142, v210
	v_add_f32_e32 v211, v94, v211
	v_add_f32_e32 v212, v126, v212
	v_add_f32_e32 v213, v110, v213
	v_add_f32_e32 v210, v143, v210
	v_add_f32_e32 v211, v95, v211
	v_add_f32_e32 v212, v127, v212
	s_waitcnt lgkmcnt(2)
	v_mfma_f32_32x32x16_bf16 v[32:47], v[228:231], v[216:219], v[32:47]
	s_waitcnt vmcnt(0) lgkmcnt(0)
	s_barrier
	s_addk_i32 s29, 0x80
	s_add_i32 s34, s34, 0x10000
	s_add_i32 s35, s35, 1
	s_cmp_eq_u32 s31, s29
	s_cbranch_scc1 .Ldiff_last
	s_add_i32 s10, s34, 0xffff0000
	s_and_b32 s36, s10, 0x10000
	s_add_i32 s10, s36, s27
	v_add_u32_e32 v248, s10, v172
	v_add_u32_e32 v249, s10, v175
	v_add_u32_e32 v237, s36, v173
	v_add_u32_e32 v236, s36, v174
	ds_read_b128 v[2:5], v248
	ds_read_b128 v[6:9], v248 offset:8192
	ds_read_b128 v[10:13], v249
	ds_read_b128 v[182:185], v249 offset:8192
	v_mfma_f32_32x32x16_bf16 v[16:31], v[232:235], v[216:219], v[16:31]
	v_add_f32_e32 v213, v111, v213
	v_add_f32_e32 v210, v210, v211
	v_add_f32_e32 v212, v212, v213
	v_fmac_f32_e32 v210, v178, v0
	v_fma_f32 v178, v210, v14, v212

; #define LAS __attribute__((address_space(3)))
; __device__ __forceinline__ unsigned cvtpk(float lo, float hi) { f32x2 v = {lo, hi}; bf16x2_t b = __builtin_convertvector(v, bf16x2_t); return __builtin_bit_cast(unsigned, b); }
; template <bool HAS_QK, bool HAS_PV> ...
;     ...
;     if (HAS_PV) {
; #pragma unroll
;         for (int ks = 2; ks < 4; ++ks)
; #pragma unroll
;             for (int c4 = 0; c4 < 4; ++c4) { const bf16x8 vf = vfrag(Vp, vb0, vb1, ks, c4); O[c4] = __builtin_amdgcn_mfma_f32_32x32x16_bf16(vf, P[ks], O[c4], 0, 0, 0); }
;     }
;     if (HAS_QK) {
;         float sum0 = 0.f, sum1 = 0.f;
; #pragma unroll
;         for (int r = 0; r < 16; ++r) { s0[r] = __builtin_amdgcn_exp2f(s0[r]); s1[r] = __builtin_amdgcn_exp2f(s1[r]); sum0 += s0[r]; sum1 += s1[r]; }
; #pragma unroll
;         for (int sp = 0; sp < 2; ++sp) {
;             u32x4 w0, w1;
;             w0.x = cvtpk(s0[8 * sp + 0], s0[8 * sp + 1]); w0.y = cvtpk(s0[8 * sp + 2], s0[8 * sp + 3]); w0.z = cvtpk(s0[8 * sp + 4], s0[8 * sp + 5]); w0.w = cvtpk(s0[8 * sp + 6], s0[8 * sp + 7]);
;             w1.x = cvtpk(s1[8 * sp + 0], s1[8 * sp + 1]); w1.y = cvtpk(s1[8 * sp + 2], s1[8 * sp + 3]); w1.z = cvtpk(s1[8 * sp + 4], s1[8 * sp + 5]); w1.w = cvtpk(s1[8 * sp + 6], s1[8 * sp + 7]);
;             P[sp] = __builtin_bit_cast(bf16x8, w0); P[2 + sp] = __builtin_bit_cast(bf16x8, w1);
;         }
;         if (need && !first) {
; #pragma unroll
;             for (int e = 0; e < 4; ++e) O[e] *= f;
;         }
;         lrun = lrun * f + (sum0 + sum1);
;     ...
;     __builtin_amdgcn_s_setprio(0);
;     const float il = __builtin_amdgcn_rcpf(xhalf_sum(lrun));
;     LAS f32x4* xb = (LAS f32x4*)(lds + qg * 16384) + lane;
;     if (cmap == 1) {
;         const float sc = il * lam;
; #pragma unroll
;         for (int e = 0; e < 4; ++e)
; #pragma unroll
;             for (int g = 0; g < 4; ++g) xb[(e * 4 + g) * 64] = (f32x4){O[e][4 * g + 0], O[e][4 * g + 1], O[e][4 * g + 2], O[e][4 * g + 3]} * sc;
;     }
.LBB0_225:
	v_cvt_pk_bf16_f32 v2, v80, v81
	v_cvt_pk_bf16_f32 v3, v82, v83
	v_cvt_pk_bf16_f32 v4, v84, v85
	v_cvt_pk_bf16_f32 v5, v86, v87
	v_cvt_pk_bf16_f32 v6, v88, v89
	v_cvt_pk_bf16_f32 v7, v90, v91
	v_cvt_pk_bf16_f32 v8, v92, v93
	v_cvt_pk_bf16_f32 v9, v94, v95
	s_andn2_b64 vcc, exec, s[4:5]
	s_waitcnt lgkmcnt(6)
	v_mfma_f32_32x32x16_bf16 v[64:79], v[220:223], v[2:5], v[64:79]
	ds_read_b64_tr_b16 v[220:221], v237 offset:28672
	ds_read_b64_tr_b16 v[222:223], v236 offset:30720
	v_exp_f32_e32 v112, v112
	v_exp_f32_e32 v113, v113
	s_waitcnt lgkmcnt(6)
	v_mfma_f32_32x32x16_bf16 v[48:63], v[224:227], v[2:5], v[48:63]
	ds_read_b64_tr_b16 v[224:225], v237 offset:29184
	ds_read_b64_tr_b16 v[226:227], v236 offset:31232
	v_exp_f32_e32 v114, v114
	v_exp_f32_e32 v115, v115
	s_waitcnt lgkmcnt(6)
	v_mfma_f32_32x32x16_bf16 v[32:47], v[228:231], v[2:5], v[32:47]
	ds_read_b64_tr_b16 v[228:229], v237 offset:29696
	ds_read_b64_tr_b16 v[230:231], v236 offset:31744
	v_exp_f32_e32 v116, v116
	v_exp_f32_e32 v117, v117
	s_waitcnt lgkmcnt(6)
	v_mfma_f32_32x32x16_bf16 v[16:31], v[232:235], v[2:5], v[16:31]
	ds_read_b64_tr_b16 v[232:233], v237 offset:30208
	ds_read_b64_tr_b16 v[234:235], v236 offset:32256
	v_exp_f32_e32 v118, v118
	v_exp_f32_e32 v119, v119
	s_waitcnt lgkmcnt(6)
	v_mfma_f32_32x32x16_bf16 v[64:79], v[220:223], v[6:9], v[64:79]
	v_exp_f32_e32 v120, v120
	v_exp_f32_e32 v121, v121
	v_cvt_pk_bf16_f32 v182, v112, v113
	s_waitcnt lgkmcnt(4)
	v_mfma_f32_32x32x16_bf16 v[48:63], v[224:227], v[6:9], v[48:63]
	v_exp_f32_e32 v122, v122
	v_exp_f32_e32 v123, v123
	v_cvt_pk_bf16_f32 v183, v114, v115
	s_waitcnt lgkmcnt(2)
	v_mfma_f32_32x32x16_bf16 v[32:47], v[228:231], v[6:9], v[32:47]
	v_exp_f32_e32 v124, v124
	v_exp_f32_e32 v125, v125
	v_cvt_pk_bf16_f32 v184, v116, v117
	s_waitcnt lgkmcnt(0)
	v_mfma_f32_32x32x16_bf16 v[16:31], v[232:235], v[6:9], v[16:31]
	v_exp_f32_e32 v126, v126
	v_exp_f32_e32 v127, v127
	v_cvt_pk_bf16_f32 v185, v118, v119
	s_cbranch_vccnz .LBB0_199
	v_pk_mul_f32 v[78:79], v[14:15], v[78:79] op_sel_hi:[0,1]
	v_pk_mul_f32 v[76:77], v[14:15], v[76:77] op_sel_hi:[0,1]
	v_pk_mul_f32 v[74:75], v[14:15], v[74:75] op_sel_hi:[0,1]
	v_pk_mul_f32 v[72:73], v[14:15], v[72:73] op_sel_hi:[0,1]
	v_pk_mul_f32 v[70:71], v[14:15], v[70:71] op_sel_hi:[0,1]
	v_pk_mul_f32 v[68:69], v[14:15], v[68:69] op_sel_hi:[0,1]
	v_pk_mul_f32 v[66:67], v[14:15], v[66:67] op_sel_hi:[0,1]
	v_pk_mul_f32 v[64:65], v[14:15], v[64:65] op_sel_hi:[0,1]
	v_pk_mul_f32 v[62:63], v[14:15], v[62:63] op_sel_hi:[0,1]
	v_pk_mul_f32 v[60:61], v[14:15], v[60:61] op_sel_hi:[0,1]
	v_pk_mul_f32 v[58:59], v[14:15], v[58:59] op_sel_hi:[0,1]
	v_pk_mul_f32 v[56:57], v[14:15], v[56:57] op_sel_hi:[0,1]
	v_pk_mul_f32 v[54:55], v[14:15], v[54:55] op_sel_hi:[0,1]
	v_pk_mul_f32 v[52:53], v[14:15], v[52:53] op_sel_hi:[0,1]
	v_pk_mul_f32 v[50:51], v[14:15], v[50:51] op_sel_hi:[0,1]
	v_pk_mul_f32 v[48:49], v[14:15], v[48:49] op_sel_hi:[0,1]
	v_pk_mul_f32 v[46:47], v[14:15], v[46:47] op_sel_hi:[0,1]
	v_pk_mul_f32 v[44:45], v[14:15], v[44:45] op_sel_hi:[0,1]
	v_pk_mul_f32 v[42:43], v[14:15], v[42:43] op_sel_hi:[0,1]
	v_pk_mul_f32 v[40:41], v[14:15], v[40:41] op_sel_hi:[0,1]
	v_pk_mul_f32 v[38:39], v[14:15], v[38:39] op_sel_hi:[0,1]
	v_pk_mul_f32 v[36:37], v[14:15], v[36:37] op_sel_hi:[0,1]
	v_pk_mul_f32 v[34:35], v[14:15], v[34:35] op_sel_hi:[0,1]
	v_pk_mul_f32 v[32:33], v[14:15], v[32:33] op_sel_hi:[0,1]
	v_pk_mul_f32 v[30:31], v[14:15], v[30:31] op_sel_hi:[0,1]
	v_pk_mul_f32 v[28:29], v[14:15], v[28:29] op_sel_hi:[0,1]
	v_pk_mul_f32 v[26:27], v[14:15], v[26:27] op_sel_hi:[0,1]
	v_pk_mul_f32 v[24:25], v[14:15], v[24:25] op_sel_hi:[0,1]
	v_pk_mul_f32 v[22:23], v[14:15], v[22:23] op_sel_hi:[0,1]
	v_pk_mul_f32 v[20:21], v[14:15], v[20:21] op_sel_hi:[0,1]
	v_pk_mul_f32 v[18:19], v[14:15], v[18:19] op_sel_hi:[0,1]
	v_pk_mul_f32 v[16:17], v[14:15], v[16:17] op_sel_hi:[0,1]
	s_branch .LBB0_199
.Ldiff_last:
	v_mfma_f32_32x32x16_bf16 v[16:31], v[232:235], v[216:219], v[16:31]
	v_add_f32_e32 v213, v111, v213
	v_add_f32_e32 v210, v210, v211
	v_add_f32_e32 v212, v212, v213
	v_fmac_f32_e32 v210, v178, v0
	v_fma_f32 v178, v210, v14, v212
.LBB0_227:
	s_setprio 0
	v_mov_b32_e32 v0, v178
	s_nop 1
	v_permlane32_swap_b32_e32 v178, v0
	v_add_f32_e32 v0, v178, v0
	v_rcp_f32_e32 v14, v0
	s_lshl_b32 s4, s19, 14
	s_add_i32 s4, s4, 0
	s_cmp_eq_u32 s18, 0
	v_lshl_add_u32 v0, v171, 4, s4
	s_cselect_b64 s[4:5], -1, 0
	s_cmp_lg_u32 s18, 0
	s_cbranch_scc0 .LBB0_229
	v_mul_f32_e32 v6, v161, v14
	v_pk_mul_f32 v[4:5], v[66:67], v[6:7] op_sel_hi:[1,0]
	v_pk_mul_f32 v[2:3], v[64:65], v[6:7] op_sel_hi:[1,0]
	ds_write_b128 v0, v[2:5]
	v_pk_mul_f32 v[4:5], v[70:71], v[6:7] op_sel_hi:[1,0]
	v_pk_mul_f32 v[2:3], v[68:69], v[6:7] op_sel_hi:[1,0]
	ds_write_b128 v0, v[2:5] offset:1024
	v_pk_mul_f32 v[4:5], v[74:75], v[6:7] op_sel_hi:[1,0]
	v_pk_mul_f32 v[2:3], v[72:73], v[6:7] op_sel_hi:[1,0]
	ds_write_b128 v0, v[2:5] offset:2048
	v_pk_mul_f32 v[4:5], v[78:79], v[6:7] op_sel_hi:[1,0]
	v_pk_mul_f32 v[2:3], v[76:77], v[6:7] op_sel_hi:[1,0]
	ds_write_b128 v0, v[2:5] offset:3072
	v_pk_mul_f32 v[4:5], v[50:51], v[6:7] op_sel_hi:[1,0]
	v_pk_mul_f32 v[2:3], v[48:49], v[6:7] op_sel_hi:[1,0]
	ds_write_b128 v0, v[2:5] offset:4096
	v_pk_mul_f32 v[4:5], v[54:55], v[6:7] op_sel_hi:[1,0]
	v_pk_mul_f32 v[2:3], v[52:53], v[6:7] op_sel_hi:[1,0]
	ds_write_b128 v0, v[2:5] offset:5120
	v_pk_mul_f32 v[4:5], v[58:59], v[6:7] op_sel_hi:[1,0]
	v_pk_mul_f32 v[2:3], v[56:57], v[6:7] op_sel_hi:[1,0]
	ds_write_b128 v0, v[2:5] offset:6144
	v_pk_mul_f32 v[4:5], v[62:63], v[6:7] op_sel_hi:[1,0]
	v_pk_mul_f32 v[2:3], v[60:61], v[6:7] op_sel_hi:[1,0]
	ds_write_b128 v0, v[2:5] offset:7168
	v_pk_mul_f32 v[4:5], v[34:35], v[6:7] op_sel_hi:[1,0]
	v_pk_mul_f32 v[2:3], v[32:33], v[6:7] op_sel_hi:[1,0]
	ds_write_b128 v0, v[2:5] offset:8192
	v_pk_mul_f32 v[4:5], v[38:39], v[6:7] op_sel_hi:[1,0]
	v_pk_mul_f32 v[2:3], v[36:37], v[6:7] op_sel_hi:[1,0]
	ds_write_b128 v0, v[2:5] offset:9216
	v_pk_mul_f32 v[4:5], v[42:43], v[6:7] op_sel_hi:[1,0]
	v_pk_mul_f32 v[2:3], v[40:41], v[6:7] op_sel_hi:[1,0]
	ds_write_b128 v0, v[2:5] offset:10240
	v_pk_mul_f32 v[4:5], v[46:47], v[6:7] op_sel_hi:[1,0]
	v_pk_mul_f32 v[2:3], v[44:45], v[6:7] op_sel_hi:[1,0]
	ds_write_b128 v0, v[2:5] offset:11264
	v_pk_mul_f32 v[4:5], v[18:19], v[6:7] op_sel_hi:[1,0]
	v_pk_mul_f32 v[2:3], v[16:17], v[6:7] op_sel_hi:[1,0]
	ds_write_b128 v0, v[2:5] offset:12288
	v_pk_mul_f32 v[4:5], v[22:23], v[6:7] op_sel_hi:[1,0]
	v_pk_mul_f32 v[2:3], v[20:21], v[6:7] op_sel_hi:[1,0]
	ds_write_b128 v0, v[2:5] offset:13312
	v_pk_mul_f32 v[4:5], v[26:27], v[6:7] op_sel_hi:[1,0]
	v_pk_mul_f32 v[2:3], v[24:25], v[6:7] op_sel_hi:[1,0]
	ds_write_b128 v0, v[2:5] offset:14336
	v_pk_mul_f32 v[4:5], v[30:31], v[6:7] op_sel_hi:[1,0]
	v_pk_mul_f32 v[2:3], v[28:29], v[6:7] op_sel_hi:[1,0]
	ds_write_b128 v0, v[2:5] offset:15360
